# v55 + K-loop back-edge rotation (7.11): loop-carried SALU updates and exit compare moved in front of the loop-back barrier in the five GEMM K-loops
# speedup vs baseline: 1.0008x; 1.0008x over previous
.LBB0_124:
	ds_read_b128 v[154:157], v168
	ds_read_b128 v[158:161], v168 offset:1024
	ds_read_b128 v[162:165], v168 offset:2048
	ds_read_b128 v[172:175], v168 offset:3072
	ds_read_b128 v[176:179], v169
	ds_read_b128 v[180:183], v169 offset:1024
	ds_read_b128 v[184:187], v169 offset:2048
	ds_read_b128 v[188:191], v169 offset:3072
	s_add_u32 s18, s16, 0xfff00080
	s_addc_u32 s19, s17, -1
	s_cmp_eq_u32 s56, 60
	s_cselect_b32 s23, s15, s19
	s_cselect_b32 s22, s21, s18
	s_cselect_b32 s19, s24, s51
	s_cselect_b32 s18, s25, s49
	s_add_i32 m0, s70, 0xc000
	ds_read_b128 v[192:195], v170
	ds_read_b128 v[196:199], v170 offset:1024
	ds_read_b128 v[200:203], v170 offset:2048
	ds_read_b128 v[204:207], v170 offset:3072
	ds_read_b128 v[208:211], v170 offset:4096
	ds_read_b128 v[212:215], v170 offset:5120
	ds_read_b128 v[216:219], v170 offset:6144
	ds_read_b128 v[220:223], v170 offset:7168
	global_load_lds_dwordx4 v146, s[16:17]
	s_add_i32 m0, s70, 0xe000
	s_nop 0
	global_load_lds_dwordx4 v148, s[16:17]
	s_waitcnt vmcnt(8)
	s_waitcnt lgkmcnt(0)
	s_barrier
	s_setprio 1
	s_waitcnt lgkmcnt(0)
	v_mfma_f32_16x16x32_bf16 v[124:127], v[154:157], v[192:195], v[124:127]
	v_mfma_f32_16x16x32_bf16 v[120:123], v[162:165], v[192:195], v[120:123]
	v_mfma_f32_16x16x32_bf16 v[108:111], v[154:157], v[200:203], v[108:111]
	v_mfma_f32_16x16x32_bf16 v[104:107], v[162:165], v[200:203], v[104:107]
	v_mfma_f32_16x16x32_bf16 v[92:95], v[154:157], v[208:211], v[92:95]
	v_mfma_f32_16x16x32_bf16 v[88:91], v[162:165], v[208:211], v[88:91]
	v_mfma_f32_16x16x32_bf16 v[76:79], v[154:157], v[216:219], v[76:79]
	v_mfma_f32_16x16x32_bf16 v[72:75], v[162:165], v[216:219], v[72:75]
	v_mfma_f32_16x16x32_bf16 v[124:127], v[158:161], v[196:199], v[124:127]
	v_mfma_f32_16x16x32_bf16 v[120:123], v[172:175], v[196:199], v[120:123]
	v_mfma_f32_16x16x32_bf16 v[108:111], v[158:161], v[204:207], v[108:111]
	v_mfma_f32_16x16x32_bf16 v[104:107], v[172:175], v[204:207], v[104:107]
	v_mfma_f32_16x16x32_bf16 v[92:95], v[158:161], v[212:215], v[92:95]
	v_mfma_f32_16x16x32_bf16 v[88:91], v[172:175], v[212:215], v[88:91]
	v_mfma_f32_16x16x32_bf16 v[76:79], v[158:161], v[220:223], v[76:79]
	v_mfma_f32_16x16x32_bf16 v[72:75], v[172:175], v[220:223], v[72:75]
	s_setprio 0
	s_setprio 1
	v_mfma_f32_16x16x32_bf16 v[116:119], v[176:179], v[192:195], v[116:119]
	v_mfma_f32_16x16x32_bf16 v[112:115], v[184:187], v[192:195], v[112:115]
	v_mfma_f32_16x16x32_bf16 v[100:103], v[176:179], v[200:203], v[100:103]
	v_mfma_f32_16x16x32_bf16 v[96:99], v[184:187], v[200:203], v[96:99]
	v_mfma_f32_16x16x32_bf16 v[84:87], v[176:179], v[208:211], v[84:87]
	v_mfma_f32_16x16x32_bf16 v[80:83], v[184:187], v[208:211], v[80:83]
	v_mfma_f32_16x16x32_bf16 v[68:71], v[176:179], v[216:219], v[68:71]
	v_mfma_f32_16x16x32_bf16 v[64:67], v[184:187], v[216:219], v[64:67]
	v_mfma_f32_16x16x32_bf16 v[116:119], v[180:183], v[196:199], v[116:119]
	v_mfma_f32_16x16x32_bf16 v[112:115], v[188:191], v[196:199], v[112:115]
	v_mfma_f32_16x16x32_bf16 v[100:103], v[180:183], v[204:207], v[100:103]
	v_mfma_f32_16x16x32_bf16 v[96:99], v[188:191], v[204:207], v[96:99]
	v_mfma_f32_16x16x32_bf16 v[84:87], v[180:183], v[212:215], v[84:87]
	v_mfma_f32_16x16x32_bf16 v[80:83], v[188:191], v[212:215], v[80:83]
	v_mfma_f32_16x16x32_bf16 v[68:71], v[180:183], v[220:223], v[68:71]
	v_mfma_f32_16x16x32_bf16 v[64:67], v[188:191], v[220:223], v[64:67]
	s_setprio 0
	s_barrier
	s_add_i32 s57, s77, s93
	s_mov_b32 m0, s57
	ds_read_b128 v[192:195], v170 offset:16384
	ds_read_b128 v[196:199], v170 offset:17408
	ds_read_b128 v[200:203], v170 offset:18432
	ds_read_b128 v[204:207], v170 offset:19456
	ds_read_b128 v[208:211], v170 offset:20480
	ds_read_b128 v[212:215], v170 offset:21504
	ds_read_b128 v[216:219], v170 offset:22528
	ds_read_b128 v[220:223], v170 offset:23552
	global_load_lds_dwordx4 v130, s[18:19]
	s_add_i32 m0, s57, 0x2000
	s_add_u32 s58, s18, 0x100000
	v_lshl_add_u64 v[224:225], s[18:19], 0, v[134:135]
	s_addc_u32 s59, s19, 0
	s_add_i32 s57, s78, s93
	global_load_lds_dwordx4 v134, s[18:19]
	s_mov_b32 m0, s57
	v_lshl_add_u64 v[228:229], s[22:23], 0, v[132:133]
	global_load_lds_dwordx4 v130, s[58:59]
	s_add_i32 m0, s57, 0x2000
	s_nop 0
	global_load_lds_dwordx4 v134, s[58:59]
	v_lshl_add_u64 v[226:227], s[22:23], 0, v[128:129]
	s_mov_b32 m0, s70
	s_nop 0
	global_load_lds_dwordx4 v128, s[22:23]
	s_mov_b32 m0, s71
	s_nop 0
	global_load_lds_dwordx4 v132, s[22:23]
	s_waitcnt vmcnt(8)
	s_waitcnt lgkmcnt(0)
	s_barrier
	s_setprio 1
	s_waitcnt lgkmcnt(0)
	v_mfma_f32_16x16x32_bf16 v[60:63], v[154:157], v[192:195], v[60:63]
	v_mfma_f32_16x16x32_bf16 v[56:59], v[162:165], v[192:195], v[56:59]
	v_mfma_f32_16x16x32_bf16 v[44:47], v[154:157], v[200:203], v[44:47]
	v_mfma_f32_16x16x32_bf16 v[40:43], v[162:165], v[200:203], v[40:43]
	v_mfma_f32_16x16x32_bf16 v[28:31], v[154:157], v[208:211], v[28:31]
	v_mfma_f32_16x16x32_bf16 v[24:27], v[162:165], v[208:211], v[24:27]
	v_mfma_f32_16x16x32_bf16 v[12:15], v[154:157], v[216:219], v[12:15]
	v_mfma_f32_16x16x32_bf16 v[8:11], v[162:165], v[216:219], v[8:11]
	v_mfma_f32_16x16x32_bf16 v[60:63], v[158:161], v[196:199], v[60:63]
	v_mfma_f32_16x16x32_bf16 v[56:59], v[172:175], v[196:199], v[56:59]
	v_mfma_f32_16x16x32_bf16 v[44:47], v[158:161], v[204:207], v[44:47]
	v_mfma_f32_16x16x32_bf16 v[40:43], v[172:175], v[204:207], v[40:43]
	v_mfma_f32_16x16x32_bf16 v[28:31], v[158:161], v[212:215], v[28:31]
	v_mfma_f32_16x16x32_bf16 v[24:27], v[172:175], v[212:215], v[24:27]
	v_mfma_f32_16x16x32_bf16 v[12:15], v[158:161], v[220:223], v[12:15]
	v_mfma_f32_16x16x32_bf16 v[8:11], v[172:175], v[220:223], v[8:11]
	s_setprio 0
	s_setprio 1
	v_mfma_f32_16x16x32_bf16 v[52:55], v[176:179], v[192:195], v[52:55]
	v_mfma_f32_16x16x32_bf16 v[48:51], v[184:187], v[192:195], v[48:51]
	v_mfma_f32_16x16x32_bf16 v[36:39], v[176:179], v[200:203], v[36:39]
	v_mfma_f32_16x16x32_bf16 v[32:35], v[184:187], v[200:203], v[32:35]
	v_mfma_f32_16x16x32_bf16 v[20:23], v[176:179], v[208:211], v[20:23]
	v_mfma_f32_16x16x32_bf16 v[16:19], v[184:187], v[208:211], v[16:19]
	v_mfma_f32_16x16x32_bf16 v[4:7], v[176:179], v[216:219], v[4:7]
	v_mfma_f32_16x16x32_bf16 v[0:3], v[184:187], v[216:219], v[0:3]
	v_mfma_f32_16x16x32_bf16 v[52:55], v[180:183], v[196:199], v[52:55]
	v_mfma_f32_16x16x32_bf16 v[48:51], v[188:191], v[196:199], v[48:51]
	v_mfma_f32_16x16x32_bf16 v[36:39], v[180:183], v[204:207], v[36:39]
	v_mfma_f32_16x16x32_bf16 v[32:35], v[188:191], v[204:207], v[32:35]
	v_mfma_f32_16x16x32_bf16 v[20:23], v[180:183], v[212:215], v[20:23]
	v_mfma_f32_16x16x32_bf16 v[16:19], v[188:191], v[212:215], v[16:19]
	v_mfma_f32_16x16x32_bf16 v[4:7], v[180:183], v[220:223], v[4:7]
	v_mfma_f32_16x16x32_bf16 v[0:3], v[188:191], v[220:223], v[0:3]
	s_setprio 0
	s_barrier
	s_add_i32 s57, 0, 0x18000
	v_add_u32_e32 v171, s57, v141
	s_add_i32 s58, 0, 0x1c000
	ds_read_b128 v[154:157], v171
	ds_read_b128 v[158:161], v171 offset:1024
	ds_read_b128 v[162:165], v171 offset:2048
	ds_read_b128 v[172:175], v171 offset:3072
	v_add_u32_e32 v171, s58, v141
	ds_read_b128 v[176:179], v171
	ds_read_b128 v[180:183], v171 offset:1024
	ds_read_b128 v[184:187], v171 offset:2048
	ds_read_b128 v[188:191], v171 offset:3072
	s_add_u32 s22, s22, 0x100000
	s_addc_u32 s23, s23, 0
	s_mov_b32 m0, s72
	ds_read_b128 v[192:195], v170 offset:32768
	ds_read_b128 v[196:199], v170 offset:33792
	ds_read_b128 v[200:203], v170 offset:34816
	ds_read_b128 v[204:207], v170 offset:35840
	ds_read_b128 v[208:211], v170 offset:36864
	ds_read_b128 v[212:215], v170 offset:37888
	ds_read_b128 v[216:219], v170 offset:38912
	ds_read_b128 v[220:223], v170 offset:39936
	global_load_lds_dwordx4 v128, s[22:23]
	s_mov_b32 m0, s73
	s_nop 0
	global_load_lds_dwordx4 v132, s[22:23]
	s_waitcnt vmcnt(8)
	s_waitcnt lgkmcnt(0)
	s_barrier
	s_setprio 1
	s_waitcnt lgkmcnt(0)
	v_mfma_f32_16x16x32_bf16 v[124:127], v[154:157], v[192:195], v[124:127]
	v_mfma_f32_16x16x32_bf16 v[120:123], v[162:165], v[192:195], v[120:123]
	v_mfma_f32_16x16x32_bf16 v[108:111], v[154:157], v[200:203], v[108:111]
	v_mfma_f32_16x16x32_bf16 v[104:107], v[162:165], v[200:203], v[104:107]
	v_mfma_f32_16x16x32_bf16 v[92:95], v[154:157], v[208:211], v[92:95]
	v_mfma_f32_16x16x32_bf16 v[88:91], v[162:165], v[208:211], v[88:91]
	v_mfma_f32_16x16x32_bf16 v[76:79], v[154:157], v[216:219], v[76:79]
	v_mfma_f32_16x16x32_bf16 v[72:75], v[162:165], v[216:219], v[72:75]
	v_mfma_f32_16x16x32_bf16 v[124:127], v[158:161], v[196:199], v[124:127]
	v_mfma_f32_16x16x32_bf16 v[120:123], v[172:175], v[196:199], v[120:123]
	v_mfma_f32_16x16x32_bf16 v[108:111], v[158:161], v[204:207], v[108:111]
	v_mfma_f32_16x16x32_bf16 v[104:107], v[172:175], v[204:207], v[104:107]
	v_mfma_f32_16x16x32_bf16 v[92:95], v[158:161], v[212:215], v[92:95]
	v_mfma_f32_16x16x32_bf16 v[88:91], v[172:175], v[212:215], v[88:91]
	v_mfma_f32_16x16x32_bf16 v[76:79], v[158:161], v[220:223], v[76:79]
	v_mfma_f32_16x16x32_bf16 v[72:75], v[172:175], v[220:223], v[72:75]
	s_setprio 0
	s_setprio 1
	v_mfma_f32_16x16x32_bf16 v[116:119], v[176:179], v[192:195], v[116:119]
	v_mfma_f32_16x16x32_bf16 v[112:115], v[184:187], v[192:195], v[112:115]
	v_mfma_f32_16x16x32_bf16 v[100:103], v[176:179], v[200:203], v[100:103]
	v_mfma_f32_16x16x32_bf16 v[96:99], v[184:187], v[200:203], v[96:99]
	v_mfma_f32_16x16x32_bf16 v[84:87], v[176:179], v[208:211], v[84:87]
	v_mfma_f32_16x16x32_bf16 v[80:83], v[184:187], v[208:211], v[80:83]
	v_mfma_f32_16x16x32_bf16 v[68:71], v[176:179], v[216:219], v[68:71]
	v_mfma_f32_16x16x32_bf16 v[64:67], v[184:187], v[216:219], v[64:67]
	v_mfma_f32_16x16x32_bf16 v[116:119], v[180:183], v[196:199], v[116:119]
	v_mfma_f32_16x16x32_bf16 v[112:115], v[188:191], v[196:199], v[112:115]
	v_mfma_f32_16x16x32_bf16 v[100:103], v[180:183], v[204:207], v[100:103]
	v_mfma_f32_16x16x32_bf16 v[96:99], v[188:191], v[204:207], v[96:99]
	v_mfma_f32_16x16x32_bf16 v[84:87], v[180:183], v[212:215], v[84:87]
	v_mfma_f32_16x16x32_bf16 v[80:83], v[188:191], v[212:215], v[80:83]
	v_mfma_f32_16x16x32_bf16 v[68:71], v[180:183], v[220:223], v[68:71]
	v_mfma_f32_16x16x32_bf16 v[64:67], v[188:191], v[220:223], v[64:67]
	s_setprio 0
	s_barrier
	s_add_i32 s22, s57, s93
	s_add_i32 m0, s22, 0xffffff80
	ds_read_b128 v[192:195], v170 offset:49152
	ds_read_b128 v[196:199], v170 offset:50176
	ds_read_b128 v[200:203], v170 offset:51200
	ds_read_b128 v[204:207], v170 offset:52224
	ds_read_b128 v[208:211], v170 offset:53248
	ds_read_b128 v[212:215], v170 offset:54272
	ds_read_b128 v[216:219], v170 offset:55296
	ds_read_b128 v[220:223], v170 offset:56320
	global_load_lds_dwordx4 v130, s[18:19] offset:128
	s_add_i32 m0, s22, 0x2000
	s_add_u32 s18, s18, 0x100080
	v_lshl_add_u64 v[166:167], v[224:225], 0, s[26:27]
	s_addc_u32 s19, s19, 0
	s_add_i32 s22, s58, s93
	global_load_lds_dwordx4 v[166:167], off
	s_mov_b32 m0, s22
	s_nop 0
	global_load_lds_dwordx4 v130, s[18:19]
	s_add_i32 m0, s22, 0x2000
	s_nop 0
	global_load_lds_dwordx4 v134, s[18:19]
	v_lshl_add_u64 v[166:167], v[226:227], 0, s[26:27]
	s_mov_b32 m0, s75
	s_nop 0
	global_load_lds_dwordx4 v[166:167], off
	v_lshl_add_u64 v[166:167], v[228:229], 0, s[26:27]
	s_mov_b32 m0, s76
	s_nop 0
	global_load_lds_dwordx4 v[166:167], off
	s_waitcnt vmcnt(8)
	s_waitcnt lgkmcnt(0)
	s_barrier
	s_setprio 1
	s_waitcnt lgkmcnt(0)
	v_mfma_f32_16x16x32_bf16 v[60:63], v[154:157], v[192:195], v[60:63]
	v_mfma_f32_16x16x32_bf16 v[56:59], v[162:165], v[192:195], v[56:59]
	v_mfma_f32_16x16x32_bf16 v[44:47], v[154:157], v[200:203], v[44:47]
	v_mfma_f32_16x16x32_bf16 v[40:43], v[162:165], v[200:203], v[40:43]
	v_mfma_f32_16x16x32_bf16 v[28:31], v[154:157], v[208:211], v[28:31]
	v_mfma_f32_16x16x32_bf16 v[24:27], v[162:165], v[208:211], v[24:27]
	v_mfma_f32_16x16x32_bf16 v[12:15], v[154:157], v[216:219], v[12:15]
	v_mfma_f32_16x16x32_bf16 v[8:11], v[162:165], v[216:219], v[8:11]
	v_mfma_f32_16x16x32_bf16 v[60:63], v[158:161], v[196:199], v[60:63]
	v_mfma_f32_16x16x32_bf16 v[56:59], v[172:175], v[196:199], v[56:59]
	v_mfma_f32_16x16x32_bf16 v[44:47], v[158:161], v[204:207], v[44:47]
	v_mfma_f32_16x16x32_bf16 v[40:43], v[172:175], v[204:207], v[40:43]
	v_mfma_f32_16x16x32_bf16 v[28:31], v[158:161], v[212:215], v[28:31]
	v_mfma_f32_16x16x32_bf16 v[24:27], v[172:175], v[212:215], v[24:27]
	v_mfma_f32_16x16x32_bf16 v[12:15], v[158:161], v[220:223], v[12:15]
	v_mfma_f32_16x16x32_bf16 v[8:11], v[172:175], v[220:223], v[8:11]
	s_setprio 0
	s_setprio 1
	v_mfma_f32_16x16x32_bf16 v[52:55], v[176:179], v[192:195], v[52:55]
	v_mfma_f32_16x16x32_bf16 v[48:51], v[184:187], v[192:195], v[48:51]
	v_mfma_f32_16x16x32_bf16 v[36:39], v[176:179], v[200:203], v[36:39]
	v_mfma_f32_16x16x32_bf16 v[32:35], v[184:187], v[200:203], v[32:35]
	v_mfma_f32_16x16x32_bf16 v[20:23], v[176:179], v[208:211], v[20:23]
	v_mfma_f32_16x16x32_bf16 v[16:19], v[184:187], v[208:211], v[16:19]
	v_mfma_f32_16x16x32_bf16 v[4:7], v[176:179], v[216:219], v[4:7]
	v_mfma_f32_16x16x32_bf16 v[0:3], v[184:187], v[216:219], v[0:3]
	v_mfma_f32_16x16x32_bf16 v[52:55], v[180:183], v[196:199], v[52:55]
	v_mfma_f32_16x16x32_bf16 v[48:51], v[188:191], v[196:199], v[48:51]
	v_mfma_f32_16x16x32_bf16 v[36:39], v[180:183], v[204:207], v[36:39]
	v_mfma_f32_16x16x32_bf16 v[32:35], v[188:191], v[204:207], v[32:35]
	v_mfma_f32_16x16x32_bf16 v[20:23], v[180:183], v[212:215], v[20:23]
	v_mfma_f32_16x16x32_bf16 v[16:19], v[188:191], v[212:215], v[16:19]
	v_mfma_f32_16x16x32_bf16 v[4:7], v[180:183], v[220:223], v[4:7]
	v_mfma_f32_16x16x32_bf16 v[0:3], v[188:191], v[220:223], v[0:3]
	s_add_i32 s56, s56, 2
	s_add_u32 s16, s16, 0x100
	s_addc_u32 s17, s17, 0
	s_add_u32 s49, s49, 0x100
	s_addc_u32 s51, s51, 0
	s_cmp_lt_u32 s56, 62
	s_setprio 0
	s_barrier
	s_cbranch_scc1 .LBB0_124
	s_andn2_b64 vcc, exec, s[94:95]
	s_cbranch_vccnz .LBB0_127
	s_barrier

.LBB0_1154:
	ds_read_b128 v[140:143], v157
	ds_read_b128 v[144:147], v157 offset:1024
	s_waitcnt lgkmcnt(0)
	ds_read_b128 v[148:151], v157 offset:2048
	ds_read_b128 v[162:165], v157 offset:3072
	ds_read_b128 v[166:169], v158
	ds_read_b128 v[170:173], v158 offset:1024
	ds_read_b128 v[174:177], v158 offset:2048
	ds_read_b128 v[178:181], v158 offset:3072
	s_add_i32 s72, s46, 2
	s_add_u32 s47, s44, 0xfff00080
	s_addc_u32 s48, s45, -1
	s_cmp_eq_u32 s75, s46
	s_cselect_b32 s46, s43, s76
	s_cselect_b32 s49, s29, s48
	s_cselect_b32 s48, s35, s47
	s_cselect_b32 s47, s31, s77
	s_add_i32 m0, s53, 0xc000
	ds_read_b128 v[182:185], v159
	ds_read_b128 v[186:189], v159 offset:1024
	ds_read_b128 v[190:193], v159 offset:2048
	ds_read_b128 v[194:197], v159 offset:3072
	ds_read_b128 v[198:201], v159 offset:4096
	ds_read_b128 v[202:205], v159 offset:5120
	ds_read_b128 v[206:209], v159 offset:6144
	ds_read_b128 v[210:213], v159 offset:7168
	global_load_lds_dwordx4 v134, s[44:45]
	s_add_i32 m0, s53, 0xe000
	s_nop 0
	global_load_lds_dwordx4 v136, s[44:45]
	s_waitcnt vmcnt(8)
	s_waitcnt lgkmcnt(0)
	s_barrier
	s_setprio 1
	s_waitcnt lgkmcnt(0)
	v_mfma_f32_16x16x32_bf16 v[124:127], v[140:143], v[182:185], v[124:127]
	v_mfma_f32_16x16x32_bf16 v[120:123], v[148:151], v[182:185], v[120:123]
	v_mfma_f32_16x16x32_bf16 v[116:119], v[140:143], v[190:193], v[116:119]
	v_mfma_f32_16x16x32_bf16 v[108:111], v[148:151], v[190:193], v[108:111]
	v_mfma_f32_16x16x32_bf16 v[100:103], v[140:143], v[198:201], v[100:103]
	v_mfma_f32_16x16x32_bf16 v[92:95], v[148:151], v[198:201], v[92:95]
	v_mfma_f32_16x16x32_bf16 v[84:87], v[140:143], v[206:209], v[84:87]
	v_mfma_f32_16x16x32_bf16 v[76:79], v[148:151], v[206:209], v[76:79]
	v_mfma_f32_16x16x32_bf16 v[124:127], v[144:147], v[186:189], v[124:127]
	v_mfma_f32_16x16x32_bf16 v[120:123], v[162:165], v[186:189], v[120:123]
	v_mfma_f32_16x16x32_bf16 v[116:119], v[144:147], v[194:197], v[116:119]
	v_mfma_f32_16x16x32_bf16 v[108:111], v[162:165], v[194:197], v[108:111]
	v_mfma_f32_16x16x32_bf16 v[100:103], v[144:147], v[202:205], v[100:103]
	v_mfma_f32_16x16x32_bf16 v[92:95], v[162:165], v[202:205], v[92:95]
	v_mfma_f32_16x16x32_bf16 v[84:87], v[144:147], v[210:213], v[84:87]
	v_mfma_f32_16x16x32_bf16 v[76:79], v[162:165], v[210:213], v[76:79]
	s_setprio 0
	s_setprio 1
	v_mfma_f32_16x16x32_bf16 v[112:115], v[166:169], v[182:185], v[112:115]
	v_mfma_f32_16x16x32_bf16 v[104:107], v[174:177], v[182:185], v[104:107]
	v_mfma_f32_16x16x32_bf16 v[96:99], v[166:169], v[190:193], v[96:99]
	v_mfma_f32_16x16x32_bf16 v[88:91], v[174:177], v[190:193], v[88:91]
	v_mfma_f32_16x16x32_bf16 v[80:83], v[166:169], v[198:201], v[80:83]
	v_mfma_f32_16x16x32_bf16 v[72:75], v[174:177], v[198:201], v[72:75]
	v_mfma_f32_16x16x32_bf16 v[68:71], v[166:169], v[206:209], v[68:71]
	v_mfma_f32_16x16x32_bf16 v[64:67], v[174:177], v[206:209], v[64:67]
	v_mfma_f32_16x16x32_bf16 v[112:115], v[170:173], v[186:189], v[112:115]
	v_mfma_f32_16x16x32_bf16 v[104:107], v[178:181], v[186:189], v[104:107]
	v_mfma_f32_16x16x32_bf16 v[96:99], v[170:173], v[194:197], v[96:99]
	v_mfma_f32_16x16x32_bf16 v[88:91], v[178:181], v[194:197], v[88:91]
	v_mfma_f32_16x16x32_bf16 v[80:83], v[170:173], v[202:205], v[80:83]
	v_mfma_f32_16x16x32_bf16 v[72:75], v[178:181], v[202:205], v[72:75]
	v_mfma_f32_16x16x32_bf16 v[68:71], v[170:173], v[210:213], v[68:71]
	v_mfma_f32_16x16x32_bf16 v[64:67], v[178:181], v[210:213], v[64:67]
	s_setprio 0
	s_barrier
	s_add_i32 s78, s62, s93
	s_mov_b32 m0, s78
	ds_read_b128 v[182:185], v159 offset:16384
	ds_read_b128 v[186:189], v159 offset:17408
	ds_read_b128 v[190:193], v159 offset:18432
	ds_read_b128 v[194:197], v159 offset:19456
	ds_read_b128 v[198:201], v159 offset:20480
	ds_read_b128 v[202:205], v159 offset:21504
	ds_read_b128 v[206:209], v159 offset:22528
	ds_read_b128 v[210:213], v159 offset:23552
	global_load_lds_dwordx4 v128, s[46:47]
	s_add_i32 m0, s78, 0x2000
	s_add_u32 s78, s46, 0x100000
	v_lshl_add_u64 v[216:217], s[46:47], 0, v[130:131]
	s_addc_u32 s79, s47, 0
	s_add_i32 s80, s63, s93
	global_load_lds_dwordx4 v130, s[46:47]
	s_mov_b32 m0, s80
	v_lshl_add_u64 v[220:221], s[48:49], 0, v[130:131]
	global_load_lds_dwordx4 v128, s[78:79]
	s_add_i32 m0, s80, 0x2000
	s_nop 0
	global_load_lds_dwordx4 v130, s[78:79]
	v_lshl_add_u64 v[218:219], s[48:49], 0, v[128:129]
	s_mov_b32 m0, s53
	s_nop 0
	global_load_lds_dwordx4 v128, s[48:49]
	s_mov_b32 m0, s54
	s_nop 0
	global_load_lds_dwordx4 v130, s[48:49]
	s_waitcnt vmcnt(8)
	s_waitcnt lgkmcnt(0)
	s_barrier
	s_setprio 1
	s_waitcnt lgkmcnt(0)
	v_mfma_f32_16x16x32_bf16 v[60:63], v[140:143], v[182:185], v[60:63]
	v_mfma_f32_16x16x32_bf16 v[56:59], v[148:151], v[182:185], v[56:59]
	v_mfma_f32_16x16x32_bf16 v[52:55], v[140:143], v[190:193], v[52:55]
	v_mfma_f32_16x16x32_bf16 v[40:43], v[148:151], v[190:193], v[40:43]
	v_mfma_f32_16x16x32_bf16 v[36:39], v[140:143], v[198:201], v[36:39]
	v_mfma_f32_16x16x32_bf16 v[24:27], v[148:151], v[198:201], v[24:27]
	v_mfma_f32_16x16x32_bf16 v[20:23], v[140:143], v[206:209], v[20:23]
	v_mfma_f32_16x16x32_bf16 v[8:11], v[148:151], v[206:209], v[8:11]
	v_mfma_f32_16x16x32_bf16 v[60:63], v[144:147], v[186:189], v[60:63]
	v_mfma_f32_16x16x32_bf16 v[56:59], v[162:165], v[186:189], v[56:59]
	v_mfma_f32_16x16x32_bf16 v[52:55], v[144:147], v[194:197], v[52:55]
	v_mfma_f32_16x16x32_bf16 v[40:43], v[162:165], v[194:197], v[40:43]
	v_mfma_f32_16x16x32_bf16 v[36:39], v[144:147], v[202:205], v[36:39]
	v_mfma_f32_16x16x32_bf16 v[24:27], v[162:165], v[202:205], v[24:27]
	v_mfma_f32_16x16x32_bf16 v[20:23], v[144:147], v[210:213], v[20:23]
	v_mfma_f32_16x16x32_bf16 v[8:11], v[162:165], v[210:213], v[8:11]
	s_setprio 0
	s_setprio 1
	v_mfma_f32_16x16x32_bf16 v[48:51], v[166:169], v[182:185], v[48:51]
	v_mfma_f32_16x16x32_bf16 v[44:47], v[174:177], v[182:185], v[44:47]
	v_mfma_f32_16x16x32_bf16 v[32:35], v[166:169], v[190:193], v[32:35]
	v_mfma_f32_16x16x32_bf16 v[28:31], v[174:177], v[190:193], v[28:31]
	v_mfma_f32_16x16x32_bf16 v[16:19], v[166:169], v[198:201], v[16:19]
	v_mfma_f32_16x16x32_bf16 v[12:15], v[174:177], v[198:201], v[12:15]
	v_mfma_f32_16x16x32_bf16 v[4:7], v[166:169], v[206:209], v[4:7]
	v_mfma_f32_16x16x32_bf16 v[0:3], v[174:177], v[206:209], v[0:3]
	v_mfma_f32_16x16x32_bf16 v[48:51], v[170:173], v[186:189], v[48:51]
	v_mfma_f32_16x16x32_bf16 v[44:47], v[178:181], v[186:189], v[44:47]
	v_mfma_f32_16x16x32_bf16 v[32:35], v[170:173], v[194:197], v[32:35]
	v_mfma_f32_16x16x32_bf16 v[28:31], v[178:181], v[194:197], v[28:31]
	v_mfma_f32_16x16x32_bf16 v[16:19], v[170:173], v[202:205], v[16:19]
	v_mfma_f32_16x16x32_bf16 v[12:15], v[178:181], v[202:205], v[12:15]
	v_mfma_f32_16x16x32_bf16 v[4:7], v[170:173], v[210:213], v[4:7]
	v_mfma_f32_16x16x32_bf16 v[0:3], v[178:181], v[210:213], v[0:3]
	s_setprio 0
	s_barrier
	s_add_i32 s78, 0, 0x18000
	v_add_u32_e32 v133, s78, v153
	s_add_i32 s79, 0, 0x1c000
	ds_read_b128 v[140:143], v133
	ds_read_b128 v[144:147], v133 offset:1024
	ds_read_b128 v[148:151], v133 offset:2048
	ds_read_b128 v[162:165], v133 offset:3072
	v_add_u32_e32 v133, s79, v153
	ds_read_b128 v[166:169], v133
	ds_read_b128 v[170:173], v133 offset:1024
	ds_read_b128 v[174:177], v133 offset:2048
	ds_read_b128 v[178:181], v133 offset:3072
	s_add_u32 s48, s48, 0x100000
	s_addc_u32 s49, s49, 0
	s_mov_b32 m0, s55
	ds_read_b128 v[182:185], v159 offset:32768
	ds_read_b128 v[186:189], v159 offset:33792
	ds_read_b128 v[190:193], v159 offset:34816
	ds_read_b128 v[194:197], v159 offset:35840
	ds_read_b128 v[198:201], v159 offset:36864
	ds_read_b128 v[202:205], v159 offset:37888
	ds_read_b128 v[206:209], v159 offset:38912
	ds_read_b128 v[210:213], v159 offset:39936
	global_load_lds_dwordx4 v128, s[48:49]
	s_mov_b32 m0, s56
	s_nop 0
	global_load_lds_dwordx4 v130, s[48:49]
	s_waitcnt vmcnt(8)
	s_waitcnt lgkmcnt(0)
	s_barrier
	s_setprio 1
	s_waitcnt lgkmcnt(0)
	v_mfma_f32_16x16x32_bf16 v[124:127], v[140:143], v[182:185], v[124:127]
	v_mfma_f32_16x16x32_bf16 v[120:123], v[148:151], v[182:185], v[120:123]
	v_mfma_f32_16x16x32_bf16 v[116:119], v[140:143], v[190:193], v[116:119]
	v_mfma_f32_16x16x32_bf16 v[108:111], v[148:151], v[190:193], v[108:111]
	v_mfma_f32_16x16x32_bf16 v[100:103], v[140:143], v[198:201], v[100:103]
	v_mfma_f32_16x16x32_bf16 v[92:95], v[148:151], v[198:201], v[92:95]
	v_mfma_f32_16x16x32_bf16 v[84:87], v[140:143], v[206:209], v[84:87]
	v_mfma_f32_16x16x32_bf16 v[76:79], v[148:151], v[206:209], v[76:79]
	v_mfma_f32_16x16x32_bf16 v[124:127], v[144:147], v[186:189], v[124:127]
	v_mfma_f32_16x16x32_bf16 v[120:123], v[162:165], v[186:189], v[120:123]
	v_mfma_f32_16x16x32_bf16 v[116:119], v[144:147], v[194:197], v[116:119]
	v_mfma_f32_16x16x32_bf16 v[108:111], v[162:165], v[194:197], v[108:111]
	v_mfma_f32_16x16x32_bf16 v[100:103], v[144:147], v[202:205], v[100:103]
	v_mfma_f32_16x16x32_bf16 v[92:95], v[162:165], v[202:205], v[92:95]
	v_mfma_f32_16x16x32_bf16 v[84:87], v[144:147], v[210:213], v[84:87]
	v_mfma_f32_16x16x32_bf16 v[76:79], v[162:165], v[210:213], v[76:79]
	s_setprio 0
	s_setprio 1
	v_mfma_f32_16x16x32_bf16 v[112:115], v[166:169], v[182:185], v[112:115]
	v_mfma_f32_16x16x32_bf16 v[104:107], v[174:177], v[182:185], v[104:107]
	v_mfma_f32_16x16x32_bf16 v[96:99], v[166:169], v[190:193], v[96:99]
	v_mfma_f32_16x16x32_bf16 v[88:91], v[174:177], v[190:193], v[88:91]
	v_mfma_f32_16x16x32_bf16 v[80:83], v[166:169], v[198:201], v[80:83]
	v_mfma_f32_16x16x32_bf16 v[72:75], v[174:177], v[198:201], v[72:75]
	v_mfma_f32_16x16x32_bf16 v[68:71], v[166:169], v[206:209], v[68:71]
	v_mfma_f32_16x16x32_bf16 v[64:67], v[174:177], v[206:209], v[64:67]
	v_mfma_f32_16x16x32_bf16 v[112:115], v[170:173], v[186:189], v[112:115]
	v_mfma_f32_16x16x32_bf16 v[104:107], v[178:181], v[186:189], v[104:107]
	v_mfma_f32_16x16x32_bf16 v[96:99], v[170:173], v[194:197], v[96:99]
	v_mfma_f32_16x16x32_bf16 v[88:91], v[178:181], v[194:197], v[88:91]
	v_mfma_f32_16x16x32_bf16 v[80:83], v[170:173], v[202:205], v[80:83]
	v_mfma_f32_16x16x32_bf16 v[72:75], v[178:181], v[202:205], v[72:75]
	v_mfma_f32_16x16x32_bf16 v[68:71], v[170:173], v[210:213], v[68:71]
	v_mfma_f32_16x16x32_bf16 v[64:67], v[178:181], v[210:213], v[64:67]
	s_setprio 0
	s_barrier
	s_add_i32 s48, s78, s93
	s_add_i32 m0, s48, 0xffffff80
	ds_read_b128 v[182:185], v159 offset:49152
	ds_read_b128 v[186:189], v159 offset:50176
	ds_read_b128 v[190:193], v159 offset:51200
	ds_read_b128 v[194:197], v159 offset:52224
	ds_read_b128 v[198:201], v159 offset:53248
	ds_read_b128 v[202:205], v159 offset:54272
	ds_read_b128 v[206:209], v159 offset:55296
	ds_read_b128 v[210:213], v159 offset:56320
	global_load_lds_dwordx4 v128, s[46:47] offset:128
	s_add_i32 m0, s48, 0x2000
	s_add_u32 s46, s46, 0x100080
	v_lshl_add_u64 v[214:215], v[216:217], 0, s[18:19]
	s_addc_u32 s47, s47, 0
	s_add_i32 s48, s79, s93
	global_load_lds_dwordx4 v[214:215], off
	s_mov_b32 m0, s48
	s_nop 0
	global_load_lds_dwordx4 v128, s[46:47]
	s_add_i32 m0, s48, 0x2000
	s_nop 0
	global_load_lds_dwordx4 v130, s[46:47]
	v_lshl_add_u64 v[214:215], v[218:219], 0, s[18:19]
	s_mov_b32 m0, s60
	s_nop 0
	global_load_lds_dwordx4 v[214:215], off
	v_lshl_add_u64 v[214:215], v[220:221], 0, s[18:19]
	s_mov_b32 m0, s61
	s_nop 0
	global_load_lds_dwordx4 v[214:215], off
	s_waitcnt vmcnt(8)
	s_waitcnt lgkmcnt(0)
	s_barrier
	s_setprio 1
	s_waitcnt lgkmcnt(0)
	v_mfma_f32_16x16x32_bf16 v[60:63], v[140:143], v[182:185], v[60:63]
	v_mfma_f32_16x16x32_bf16 v[56:59], v[148:151], v[182:185], v[56:59]
	v_mfma_f32_16x16x32_bf16 v[52:55], v[140:143], v[190:193], v[52:55]
	v_mfma_f32_16x16x32_bf16 v[40:43], v[148:151], v[190:193], v[40:43]
	v_mfma_f32_16x16x32_bf16 v[36:39], v[140:143], v[198:201], v[36:39]
	v_mfma_f32_16x16x32_bf16 v[24:27], v[148:151], v[198:201], v[24:27]
	v_mfma_f32_16x16x32_bf16 v[20:23], v[140:143], v[206:209], v[20:23]
	v_mfma_f32_16x16x32_bf16 v[8:11], v[148:151], v[206:209], v[8:11]
	v_mfma_f32_16x16x32_bf16 v[60:63], v[144:147], v[186:189], v[60:63]
	v_mfma_f32_16x16x32_bf16 v[56:59], v[162:165], v[186:189], v[56:59]
	v_mfma_f32_16x16x32_bf16 v[52:55], v[144:147], v[194:197], v[52:55]
	v_mfma_f32_16x16x32_bf16 v[40:43], v[162:165], v[194:197], v[40:43]
	v_mfma_f32_16x16x32_bf16 v[36:39], v[144:147], v[202:205], v[36:39]
	v_mfma_f32_16x16x32_bf16 v[24:27], v[162:165], v[202:205], v[24:27]
	v_mfma_f32_16x16x32_bf16 v[20:23], v[144:147], v[210:213], v[20:23]
	v_mfma_f32_16x16x32_bf16 v[8:11], v[162:165], v[210:213], v[8:11]
	s_setprio 0
	s_setprio 1
	v_mfma_f32_16x16x32_bf16 v[48:51], v[166:169], v[182:185], v[48:51]
	v_mfma_f32_16x16x32_bf16 v[44:47], v[174:177], v[182:185], v[44:47]
	v_mfma_f32_16x16x32_bf16 v[32:35], v[166:169], v[190:193], v[32:35]
	v_mfma_f32_16x16x32_bf16 v[28:31], v[174:177], v[190:193], v[28:31]
	v_mfma_f32_16x16x32_bf16 v[16:19], v[166:169], v[198:201], v[16:19]
	v_mfma_f32_16x16x32_bf16 v[12:15], v[174:177], v[198:201], v[12:15]
	v_mfma_f32_16x16x32_bf16 v[4:7], v[166:169], v[206:209], v[4:7]
	v_mfma_f32_16x16x32_bf16 v[0:3], v[174:177], v[206:209], v[0:3]
	v_mfma_f32_16x16x32_bf16 v[48:51], v[170:173], v[186:189], v[48:51]
	v_mfma_f32_16x16x32_bf16 v[44:47], v[178:181], v[186:189], v[44:47]
	v_mfma_f32_16x16x32_bf16 v[32:35], v[170:173], v[194:197], v[32:35]
	v_mfma_f32_16x16x32_bf16 v[28:31], v[178:181], v[194:197], v[28:31]
	v_mfma_f32_16x16x32_bf16 v[16:19], v[170:173], v[202:205], v[16:19]
	v_mfma_f32_16x16x32_bf16 v[12:15], v[178:181], v[202:205], v[12:15]
	v_mfma_f32_16x16x32_bf16 v[4:7], v[170:173], v[210:213], v[4:7]
	v_mfma_f32_16x16x32_bf16 v[0:3], v[178:181], v[210:213], v[0:3]
	s_add_u32 s44, s44, 0x100
	s_addc_u32 s45, s45, 0
	s_add_u32 s76, s76, 0x100
	s_addc_u32 s77, s77, 0
	s_cmp_lt_i32 s72, s27
	s_mov_b32 s46, s72
	s_setprio 0
	s_barrier
	s_cbranch_scc1 .LBB0_1154
	s_andn2_b64 vcc, exec, s[94:95]
	s_cbranch_vccnz .LBB0_1157
	s_barrier

.LBB0_1297:
	v_add_u32_e32 v154, s80, v181
	v_add_u32_e32 v170, s81, v181
	ds_read_b128 v[142:145], v154
	ds_read_b128 v[146:149], v154 offset:1024
	ds_read_b128 v[150:153], v154 offset:2048
	ds_read_b128 v[154:157], v154 offset:3072
	ds_read_b128 v[158:161], v170
	ds_read_b128 v[162:165], v170 offset:1024
	ds_read_b128 v[166:169], v170 offset:2048
	ds_read_b128 v[170:173], v170 offset:3072
	s_add_i32 s72, s62, 2
	s_add_u32 s24, s60, 0xfff80080
	s_addc_u32 s25, s61, -1
	s_cmp_eq_u32 s97, s62
	s_cselect_b32 s62, s96, vcc_lo
	s_cselect_b32 s65, s41, s25
	s_cselect_b32 s64, s45, s24
	s_cselect_b32 s63, s43, vcc_hi
	s_add_i32 m0, s55, 0xc000
	ds_read_b128 v[174:177], v183
	ds_read_b128 v[184:187], v183 offset:1024
	ds_read_b128 v[188:191], v183 offset:2048
	ds_read_b128 v[192:195], v183 offset:3072
	ds_read_b128 v[196:199], v183 offset:4096
	ds_read_b128 v[200:203], v183 offset:5120
	ds_read_b128 v[204:207], v183 offset:6144
	ds_read_b128 v[208:211], v183 offset:7168
	global_load_lds_dwordx4 v138, s[60:61]
	s_add_i32 m0, s55, 0xe000
	s_nop 0
	global_load_lds_dwordx4 v140, s[60:61]
	s_waitcnt vmcnt(8)
	s_waitcnt lgkmcnt(0)
	s_barrier
	s_setprio 1
	s_waitcnt lgkmcnt(0)
	v_mfma_i32_16x16x64_i8 v[124:127], v[142:145], v[174:177], v[124:127]
	v_mfma_i32_16x16x64_i8 v[120:123], v[150:153], v[174:177], v[120:123]
	v_mfma_i32_16x16x64_i8 v[116:119], v[142:145], v[188:191], v[116:119]
	v_mfma_i32_16x16x64_i8 v[112:115], v[150:153], v[188:191], v[112:115]
	v_mfma_i32_16x16x64_i8 v[104:107], v[142:145], v[196:199], v[104:107]
	v_mfma_i32_16x16x64_i8 v[96:99], v[150:153], v[196:199], v[96:99]
	v_mfma_i32_16x16x64_i8 v[88:91], v[142:145], v[204:207], v[88:91]
	v_mfma_i32_16x16x64_i8 v[80:83], v[150:153], v[204:207], v[80:83]
	v_mfma_i32_16x16x64_i8 v[124:127], v[146:149], v[184:187], v[124:127]
	v_mfma_i32_16x16x64_i8 v[120:123], v[154:157], v[184:187], v[120:123]
	v_mfma_i32_16x16x64_i8 v[116:119], v[146:149], v[192:195], v[116:119]
	v_mfma_i32_16x16x64_i8 v[112:115], v[154:157], v[192:195], v[112:115]
	v_mfma_i32_16x16x64_i8 v[104:107], v[146:149], v[200:203], v[104:107]
	v_mfma_i32_16x16x64_i8 v[96:99], v[154:157], v[200:203], v[96:99]
	v_mfma_i32_16x16x64_i8 v[88:91], v[146:149], v[208:211], v[88:91]
	v_mfma_i32_16x16x64_i8 v[80:83], v[154:157], v[208:211], v[80:83]
	s_setprio 0
	s_setprio 1
	v_mfma_i32_16x16x64_i8 v[108:111], v[158:161], v[174:177], v[108:111]
	v_mfma_i32_16x16x64_i8 v[100:103], v[166:169], v[174:177], v[100:103]
	v_mfma_i32_16x16x64_i8 v[92:95], v[158:161], v[188:191], v[92:95]
	v_mfma_i32_16x16x64_i8 v[84:87], v[166:169], v[188:191], v[84:87]
	v_mfma_i32_16x16x64_i8 v[76:79], v[158:161], v[196:199], v[76:79]
	v_mfma_i32_16x16x64_i8 v[72:75], v[166:169], v[196:199], v[72:75]
	v_mfma_i32_16x16x64_i8 v[68:71], v[158:161], v[204:207], v[68:71]
	v_mfma_i32_16x16x64_i8 v[64:67], v[166:169], v[204:207], v[64:67]
	v_mfma_i32_16x16x64_i8 v[108:111], v[162:165], v[184:187], v[108:111]
	v_mfma_i32_16x16x64_i8 v[100:103], v[170:173], v[184:187], v[100:103]
	v_mfma_i32_16x16x64_i8 v[92:95], v[162:165], v[192:195], v[92:95]
	v_mfma_i32_16x16x64_i8 v[84:87], v[170:173], v[192:195], v[84:87]
	v_mfma_i32_16x16x64_i8 v[76:79], v[162:165], v[200:203], v[76:79]
	v_mfma_i32_16x16x64_i8 v[72:75], v[170:173], v[200:203], v[72:75]
	v_mfma_i32_16x16x64_i8 v[68:71], v[162:165], v[208:211], v[68:71]
	v_mfma_i32_16x16x64_i8 v[64:67], v[170:173], v[208:211], v[64:67]
	s_setprio 0
	s_barrier
	s_add_i32 s24, s80, s93
	s_mov_b32 m0, s24
	ds_read_b128 v[174:177], v183 offset:16384
	ds_read_b128 v[184:187], v183 offset:17408
	ds_read_b128 v[188:191], v183 offset:18432
	ds_read_b128 v[192:195], v183 offset:19456
	ds_read_b128 v[196:199], v183 offset:20480
	ds_read_b128 v[200:203], v183 offset:21504
	ds_read_b128 v[204:207], v183 offset:22528
	ds_read_b128 v[208:211], v183 offset:23552
	global_load_lds_dwordx4 v130, s[62:63]
	s_add_i32 m0, s24, 0x2000
	s_add_u32 s24, s62, 0x80000
	v_lshl_add_u64 v[212:213], s[62:63], 0, v[134:135]
	s_addc_u32 s25, s63, 0
	s_add_i32 s73, s81, s93
	global_load_lds_dwordx4 v134, s[62:63]
	s_mov_b32 m0, s73
	s_nop 0
	global_load_lds_dwordx4 v130, s[24:25]
	s_add_i32 m0, s73, 0x2000
	s_nop 0
	global_load_lds_dwordx4 v134, s[24:25]
	s_mov_b32 m0, s55
	s_nop 0
	global_load_lds_dwordx4 v128, s[64:65]
	s_mov_b32 m0, s57
	s_nop 0
	global_load_lds_dwordx4 v132, s[64:65]
	s_waitcnt vmcnt(8)
	s_waitcnt lgkmcnt(0)
	s_barrier
	s_setprio 1
	s_waitcnt lgkmcnt(0)
	v_mfma_i32_16x16x64_i8 v[60:63], v[142:145], v[174:177], v[60:63]
	v_mfma_i32_16x16x64_i8 v[56:59], v[150:153], v[174:177], v[56:59]
	v_mfma_i32_16x16x64_i8 v[52:55], v[142:145], v[188:191], v[52:55]
	v_mfma_i32_16x16x64_i8 v[48:51], v[150:153], v[188:191], v[48:51]
	v_mfma_i32_16x16x64_i8 v[44:47], v[142:145], v[196:199], v[44:47]
	v_mfma_i32_16x16x64_i8 v[40:43], v[150:153], v[196:199], v[40:43]
	v_mfma_i32_16x16x64_i8 v[36:39], v[142:145], v[204:207], v[36:39]
	v_mfma_i32_16x16x64_i8 v[32:35], v[150:153], v[204:207], v[32:35]
	v_mfma_i32_16x16x64_i8 v[60:63], v[146:149], v[184:187], v[60:63]
	v_mfma_i32_16x16x64_i8 v[56:59], v[154:157], v[184:187], v[56:59]
	v_mfma_i32_16x16x64_i8 v[52:55], v[146:149], v[192:195], v[52:55]
	v_mfma_i32_16x16x64_i8 v[48:51], v[154:157], v[192:195], v[48:51]
	v_mfma_i32_16x16x64_i8 v[44:47], v[146:149], v[200:203], v[44:47]
	v_mfma_i32_16x16x64_i8 v[40:43], v[154:157], v[200:203], v[40:43]
	v_mfma_i32_16x16x64_i8 v[36:39], v[146:149], v[208:211], v[36:39]
	v_mfma_i32_16x16x64_i8 v[32:35], v[154:157], v[208:211], v[32:35]
	s_setprio 0
	s_setprio 1
	v_mfma_i32_16x16x64_i8 v[28:31], v[158:161], v[174:177], v[28:31]
	v_mfma_i32_16x16x64_i8 v[24:27], v[166:169], v[174:177], v[24:27]
	v_mfma_i32_16x16x64_i8 v[20:23], v[158:161], v[188:191], v[20:23]
	v_mfma_i32_16x16x64_i8 v[16:19], v[166:169], v[188:191], v[16:19]
	v_mfma_i32_16x16x64_i8 v[12:15], v[158:161], v[196:199], v[12:15]
	v_mfma_i32_16x16x64_i8 v[8:11], v[166:169], v[196:199], v[8:11]
	v_mfma_i32_16x16x64_i8 v[4:7], v[158:161], v[204:207], v[4:7]
	v_mfma_i32_16x16x64_i8 v[0:3], v[166:169], v[204:207], v[0:3]
	v_mfma_i32_16x16x64_i8 v[28:31], v[162:165], v[184:187], v[28:31]
	v_mfma_i32_16x16x64_i8 v[24:27], v[170:173], v[184:187], v[24:27]
	v_mfma_i32_16x16x64_i8 v[20:23], v[162:165], v[192:195], v[20:23]
	v_mfma_i32_16x16x64_i8 v[16:19], v[170:173], v[192:195], v[16:19]
	v_mfma_i32_16x16x64_i8 v[12:15], v[162:165], v[200:203], v[12:15]
	v_mfma_i32_16x16x64_i8 v[8:11], v[170:173], v[200:203], v[8:11]
	v_mfma_i32_16x16x64_i8 v[4:7], v[162:165], v[208:211], v[4:7]
	v_mfma_i32_16x16x64_i8 v[0:3], v[170:173], v[208:211], v[0:3]
	s_setprio 0
	s_barrier
	s_add_i32 s73, 0, 0x18000
	s_add_i32 s66, 0, 0x1c000
	v_add_u32_e32 v154, s73, v181
	v_add_u32_e32 v170, s66, v181
	ds_read_b128 v[142:145], v154
	ds_read_b128 v[146:149], v154 offset:1024
	ds_read_b128 v[150:153], v154 offset:2048
	ds_read_b128 v[154:157], v154 offset:3072
	ds_read_b128 v[158:161], v170
	ds_read_b128 v[162:165], v170 offset:1024
	ds_read_b128 v[166:169], v170 offset:2048
	ds_read_b128 v[170:173], v170 offset:3072
	s_add_u32 s24, s64, 0x80000
	s_addc_u32 s25, s65, 0
	s_mov_b32 m0, s69
	ds_read_b128 v[174:177], v183 offset:32768
	ds_read_b128 v[184:187], v183 offset:33792
	ds_read_b128 v[188:191], v183 offset:34816
	ds_read_b128 v[192:195], v183 offset:35840
	ds_read_b128 v[196:199], v183 offset:36864
	ds_read_b128 v[200:203], v183 offset:37888
	ds_read_b128 v[204:207], v183 offset:38912
	ds_read_b128 v[208:211], v183 offset:39936
	global_load_lds_dwordx4 v128, s[24:25]
	s_mov_b32 m0, s74
	s_nop 0
	global_load_lds_dwordx4 v132, s[24:25]
	s_waitcnt vmcnt(8)
	s_waitcnt lgkmcnt(0)
	s_barrier
	s_setprio 1
	s_waitcnt lgkmcnt(0)
	v_mfma_i32_16x16x64_i8 v[124:127], v[142:145], v[174:177], v[124:127]
	v_mfma_i32_16x16x64_i8 v[120:123], v[150:153], v[174:177], v[120:123]
	v_mfma_i32_16x16x64_i8 v[116:119], v[142:145], v[188:191], v[116:119]
	v_mfma_i32_16x16x64_i8 v[112:115], v[150:153], v[188:191], v[112:115]
	v_mfma_i32_16x16x64_i8 v[104:107], v[142:145], v[196:199], v[104:107]
	v_mfma_i32_16x16x64_i8 v[96:99], v[150:153], v[196:199], v[96:99]
	v_mfma_i32_16x16x64_i8 v[88:91], v[142:145], v[204:207], v[88:91]
	v_mfma_i32_16x16x64_i8 v[80:83], v[150:153], v[204:207], v[80:83]
	v_mfma_i32_16x16x64_i8 v[124:127], v[146:149], v[184:187], v[124:127]
	v_mfma_i32_16x16x64_i8 v[120:123], v[154:157], v[184:187], v[120:123]
	v_mfma_i32_16x16x64_i8 v[116:119], v[146:149], v[192:195], v[116:119]
	v_mfma_i32_16x16x64_i8 v[112:115], v[154:157], v[192:195], v[112:115]
	v_mfma_i32_16x16x64_i8 v[104:107], v[146:149], v[200:203], v[104:107]
	v_mfma_i32_16x16x64_i8 v[96:99], v[154:157], v[200:203], v[96:99]
	v_mfma_i32_16x16x64_i8 v[88:91], v[146:149], v[208:211], v[88:91]
	v_mfma_i32_16x16x64_i8 v[80:83], v[154:157], v[208:211], v[80:83]
	s_setprio 0
	s_setprio 1
	v_mfma_i32_16x16x64_i8 v[108:111], v[158:161], v[174:177], v[108:111]
	v_mfma_i32_16x16x64_i8 v[100:103], v[166:169], v[174:177], v[100:103]
	v_mfma_i32_16x16x64_i8 v[92:95], v[158:161], v[188:191], v[92:95]
	v_mfma_i32_16x16x64_i8 v[84:87], v[166:169], v[188:191], v[84:87]
	v_mfma_i32_16x16x64_i8 v[76:79], v[158:161], v[196:199], v[76:79]
	v_mfma_i32_16x16x64_i8 v[72:75], v[166:169], v[196:199], v[72:75]
	v_mfma_i32_16x16x64_i8 v[68:71], v[158:161], v[204:207], v[68:71]
	v_mfma_i32_16x16x64_i8 v[64:67], v[166:169], v[204:207], v[64:67]
	v_mfma_i32_16x16x64_i8 v[108:111], v[162:165], v[184:187], v[108:111]
	v_mfma_i32_16x16x64_i8 v[100:103], v[170:173], v[184:187], v[100:103]
	v_mfma_i32_16x16x64_i8 v[92:95], v[162:165], v[192:195], v[92:95]
	v_mfma_i32_16x16x64_i8 v[84:87], v[170:173], v[192:195], v[84:87]
	v_mfma_i32_16x16x64_i8 v[76:79], v[162:165], v[200:203], v[76:79]
	v_mfma_i32_16x16x64_i8 v[72:75], v[170:173], v[200:203], v[72:75]
	v_mfma_i32_16x16x64_i8 v[68:71], v[162:165], v[208:211], v[68:71]
	v_mfma_i32_16x16x64_i8 v[64:67], v[170:173], v[208:211], v[64:67]
	s_setprio 0
	s_barrier
	s_add_i32 s24, s73, s93
	s_add_i32 m0, s24, 0xffffff80
	ds_read_b128 v[174:177], v183 offset:49152
	ds_read_b128 v[184:187], v183 offset:50176
	ds_read_b128 v[188:191], v183 offset:51200
	ds_read_b128 v[192:195], v183 offset:52224
	ds_read_b128 v[196:199], v183 offset:53248
	ds_read_b128 v[200:203], v183 offset:54272
	ds_read_b128 v[204:207], v183 offset:55296
	ds_read_b128 v[208:211], v183 offset:56320
	global_load_lds_dwordx4 v130, s[62:63] offset:128
	s_add_i32 m0, s24, 0x2000
	s_add_u32 s24, s62, 0x80080
	v_lshl_add_u64 v[178:179], v[212:213], 0, s[38:39]
	s_addc_u32 s25, s63, 0
	s_add_i32 s62, s66, s93
	global_load_lds_dwordx4 v[178:179], off
	s_mov_b32 m0, s62
	s_nop 0
	global_load_lds_dwordx4 v130, s[24:25]
	s_add_i32 m0, s62, 0x2000
	s_nop 0
	global_load_lds_dwordx4 v134, s[24:25]
	s_add_i32 m0, s77, 0xffffff80
	s_nop 0
	global_load_lds_dwordx4 v128, s[64:65] offset:128
	s_add_i32 m0, s78, 0xffffff80
	s_nop 0
	global_load_lds_dwordx4 v132, s[64:65] offset:128
	s_waitcnt vmcnt(8)
	s_waitcnt lgkmcnt(0)
	s_barrier
	s_setprio 1
	s_waitcnt lgkmcnt(0)
	v_mfma_i32_16x16x64_i8 v[60:63], v[142:145], v[174:177], v[60:63]
	v_mfma_i32_16x16x64_i8 v[56:59], v[150:153], v[174:177], v[56:59]
	v_mfma_i32_16x16x64_i8 v[52:55], v[142:145], v[188:191], v[52:55]
	v_mfma_i32_16x16x64_i8 v[48:51], v[150:153], v[188:191], v[48:51]
	v_mfma_i32_16x16x64_i8 v[44:47], v[142:145], v[196:199], v[44:47]
	v_mfma_i32_16x16x64_i8 v[40:43], v[150:153], v[196:199], v[40:43]
	v_mfma_i32_16x16x64_i8 v[36:39], v[142:145], v[204:207], v[36:39]
	v_mfma_i32_16x16x64_i8 v[32:35], v[150:153], v[204:207], v[32:35]
	v_mfma_i32_16x16x64_i8 v[60:63], v[146:149], v[184:187], v[60:63]
	v_mfma_i32_16x16x64_i8 v[56:59], v[154:157], v[184:187], v[56:59]
	v_mfma_i32_16x16x64_i8 v[52:55], v[146:149], v[192:195], v[52:55]
	v_mfma_i32_16x16x64_i8 v[48:51], v[154:157], v[192:195], v[48:51]
	v_mfma_i32_16x16x64_i8 v[44:47], v[146:149], v[200:203], v[44:47]
	v_mfma_i32_16x16x64_i8 v[40:43], v[154:157], v[200:203], v[40:43]
	v_mfma_i32_16x16x64_i8 v[36:39], v[146:149], v[208:211], v[36:39]
	v_mfma_i32_16x16x64_i8 v[32:35], v[154:157], v[208:211], v[32:35]
	s_setprio 0
	s_setprio 1
	v_mfma_i32_16x16x64_i8 v[28:31], v[158:161], v[174:177], v[28:31]
	v_mfma_i32_16x16x64_i8 v[24:27], v[166:169], v[174:177], v[24:27]
	v_mfma_i32_16x16x64_i8 v[20:23], v[158:161], v[188:191], v[20:23]
	v_mfma_i32_16x16x64_i8 v[16:19], v[166:169], v[188:191], v[16:19]
	v_mfma_i32_16x16x64_i8 v[12:15], v[158:161], v[196:199], v[12:15]
	v_mfma_i32_16x16x64_i8 v[8:11], v[166:169], v[196:199], v[8:11]
	v_mfma_i32_16x16x64_i8 v[4:7], v[158:161], v[204:207], v[4:7]
	v_mfma_i32_16x16x64_i8 v[0:3], v[166:169], v[204:207], v[0:3]
	v_mfma_i32_16x16x64_i8 v[28:31], v[162:165], v[184:187], v[28:31]
	v_mfma_i32_16x16x64_i8 v[24:27], v[170:173], v[184:187], v[24:27]
	v_mfma_i32_16x16x64_i8 v[20:23], v[162:165], v[192:195], v[20:23]
	v_mfma_i32_16x16x64_i8 v[16:19], v[170:173], v[192:195], v[16:19]
	v_mfma_i32_16x16x64_i8 v[12:15], v[162:165], v[200:203], v[12:15]
	v_mfma_i32_16x16x64_i8 v[8:11], v[170:173], v[200:203], v[8:11]
	v_mfma_i32_16x16x64_i8 v[4:7], v[162:165], v[208:211], v[4:7]
	v_mfma_i32_16x16x64_i8 v[0:3], v[170:173], v[208:211], v[0:3]
	s_add_u32 s60, s60, 0x100
	s_addc_u32 s61, s61, 0
	s_add_u32 vcc_lo, vcc_lo, 0x100
	s_addc_u32 vcc_hi, vcc_hi, 0
	s_cmp_ge_i32 s72, s91
	s_mov_b32 s62, s72
	s_setprio 0
	s_barrier
	s_cbranch_scc0 .LBB0_1297
	s_andn2_b64 vcc, exec, s[58:59]
	s_cbranch_vccnz .LBB0_1311
	global_load_dword v142, v131, s[10:11] sc1
	s_waitcnt vmcnt(0)
	v_cmp_lt_u32_e32 vcc, s7, v142
	s_cbranch_vccnz .LBB0_1310
	s_mov_b32 s41, 0x3ffff8
	s_branch .LBB0_1302

.LBB0_1444:
	ds_read_b128 v[24:27], v191
	ds_read_b128 v[28:31], v191 offset:1024
	ds_read_b128 v[16:19], v191 offset:2048
	ds_read_b128 v[20:23], v191 offset:3072
	ds_read_b128 v[8:11], v192
	ds_read_b128 v[12:15], v192 offset:1024
	s_waitcnt lgkmcnt(0)
	ds_read_b128 v[0:3], v192 offset:2048
	ds_read_b128 v[4:7], v192 offset:3072
	s_add_i32 vcc_hi, s62, 2
	s_add_u32 s60, s58, 0x100
	s_addc_u32 s61, s59, 0
	s_cmp_eq_u32 s53, s62
	s_cselect_b32 s62, s56, s97
	s_cselect_b32 s65, s55, s61
	s_cselect_b32 s64, s54, s60
	s_cselect_b32 s63, s57, vcc_lo
	s_add_i32 m0, s31, 0xc000
	ds_read_b128 v[172:175], v193
	ds_read_b128 v[176:179], v193 offset:1024
	ds_read_b128 v[194:197], v193 offset:2048
	ds_read_b128 v[198:201], v193 offset:3072
	ds_read_b128 v[202:205], v193 offset:4096
	ds_read_b128 v[206:209], v193 offset:5120
	ds_read_b128 v[210:213], v193 offset:6144
	ds_read_b128 v[214:217], v193 offset:7168
	global_load_lds_dwordx4 v166, s[58:59]
	s_add_i32 m0, s31, 0xe000
	s_nop 0
	global_load_lds_dwordx4 v168, s[58:59]
	s_waitcnt vmcnt(8)
	s_waitcnt lgkmcnt(0)
	s_barrier
	s_setprio 1
	s_waitcnt lgkmcnt(0)
	v_mfma_f32_16x16x128_f8f6f4 v[156:159], v[24:31], v[172:179], v[156:159]
	v_mfma_f32_16x16x128_f8f6f4 v[152:155], v[16:23], v[172:179], v[152:155]
	v_mfma_f32_16x16x128_f8f6f4 v[148:151], v[24:31], v[194:201], v[148:151]
	v_mfma_f32_16x16x128_f8f6f4 v[140:143], v[16:23], v[194:201], v[140:143]
	v_mfma_f32_16x16x128_f8f6f4 v[132:135], v[24:31], v[202:209], v[132:135]
	v_mfma_f32_16x16x128_f8f6f4 v[124:127], v[16:23], v[202:209], v[124:127]
	v_mfma_f32_16x16x128_f8f6f4 v[116:119], v[24:31], v[210:217], v[116:119]
	v_mfma_f32_16x16x128_f8f6f4 v[108:111], v[16:23], v[210:217], v[108:111]
	s_setprio 0
	s_setprio 1
	v_mfma_f32_16x16x128_f8f6f4 v[144:147], v[8:15], v[172:179], v[144:147]
	v_mfma_f32_16x16x128_f8f6f4 v[136:139], v[0:7], v[172:179], v[136:139]
	v_mfma_f32_16x16x128_f8f6f4 v[128:131], v[8:15], v[194:201], v[128:131]
	v_mfma_f32_16x16x128_f8f6f4 v[120:123], v[0:7], v[194:201], v[120:123]
	v_mfma_f32_16x16x128_f8f6f4 v[112:115], v[8:15], v[202:209], v[112:115]
	v_mfma_f32_16x16x128_f8f6f4 v[104:107], v[0:7], v[202:209], v[104:107]
	v_mfma_f32_16x16x128_f8f6f4 v[100:103], v[8:15], v[210:217], v[100:103]
	v_mfma_f32_16x16x128_f8f6f4 v[96:99], v[0:7], v[210:217], v[96:99]
	s_setprio 0
	s_barrier
	s_add_i32 s24, s82, s93
	s_mov_b32 m0, s24
	ds_read_b128 v[194:197], v193 offset:16384
	ds_read_b128 v[198:201], v193 offset:17408
	ds_read_b128 v[202:205], v193 offset:18432
	ds_read_b128 v[206:209], v193 offset:19456
	ds_read_b128 v[210:213], v193 offset:20480
	ds_read_b128 v[214:217], v193 offset:21504
	ds_read_b128 v[218:221], v193 offset:22528
	ds_read_b128 v[222:225], v193 offset:23552
	global_load_lds_dwordx4 v160, s[62:63]
	s_add_i32 m0, s24, 0x2000
	s_add_u32 s24, s62, 0x158000
	s_addc_u32 s25, s63, 0
	s_add_i32 s58, s83, s93
	global_load_lds_dwordx4 v162, s[62:63]
	s_mov_b32 m0, s58
	s_nop 0
	global_load_lds_dwordx4 v160, s[24:25]
	s_add_i32 m0, s58, 0x2000
	s_nop 0
	global_load_lds_dwordx4 v162, s[24:25]
	s_mov_b32 m0, s31
	s_nop 0
	global_load_lds_dwordx4 v160, s[64:65]
	s_mov_b32 m0, s47
	s_nop 0
	global_load_lds_dwordx4 v162, s[64:65]
	s_waitcnt vmcnt(8)
	s_waitcnt lgkmcnt(0)
	s_barrier
	s_setprio 1
	s_waitcnt lgkmcnt(0)
	v_mfma_f32_16x16x128_f8f6f4 v[92:95], v[24:31], v[194:201], v[92:95]
	v_mfma_f32_16x16x128_f8f6f4 v[88:91], v[16:23], v[194:201], v[88:91]
	v_mfma_f32_16x16x128_f8f6f4 v[84:87], v[24:31], v[202:209], v[84:87]
	v_mfma_f32_16x16x128_f8f6f4 v[72:75], v[16:23], v[202:209], v[72:75]
	v_mfma_f32_16x16x128_f8f6f4 v[68:71], v[24:31], v[210:217], v[68:71]
	v_mfma_f32_16x16x128_f8f6f4 v[56:59], v[16:23], v[210:217], v[56:59]
	v_mfma_f32_16x16x128_f8f6f4 v[52:55], v[24:31], v[218:225], v[52:55]
	v_mfma_f32_16x16x128_f8f6f4 v[40:43], v[16:23], v[218:225], v[40:43]
	s_setprio 0
	s_setprio 1
	v_mfma_f32_16x16x128_f8f6f4 v[80:83], v[8:15], v[194:201], v[80:83]
	v_mfma_f32_16x16x128_f8f6f4 v[76:79], v[0:7], v[194:201], v[76:79]
	v_mfma_f32_16x16x128_f8f6f4 v[64:67], v[8:15], v[202:209], v[64:67]
	v_mfma_f32_16x16x128_f8f6f4 v[60:63], v[0:7], v[202:209], v[60:63]
	v_mfma_f32_16x16x128_f8f6f4 v[48:51], v[8:15], v[210:217], v[48:51]
	v_mfma_f32_16x16x128_f8f6f4 v[44:47], v[0:7], v[210:217], v[44:47]
	v_mfma_f32_16x16x128_f8f6f4 v[36:39], v[8:15], v[218:225], v[36:39]
	v_mfma_f32_16x16x128_f8f6f4 v[32:35], v[0:7], v[218:225], v[32:35]
	s_setprio 0
	s_barrier
	s_add_i32 s58, 0, 0x18000
	s_add_i32 s59, 0, 0x1c000
	v_add_u32_e32 v12, s58, v187
	v_add_u32_e32 v28, s59, v187
	ds_read_b128 v[0:3], v12
	ds_read_b128 v[4:7], v12 offset:1024
	ds_read_b128 v[8:11], v12 offset:2048
	ds_read_b128 v[12:15], v12 offset:3072
	ds_read_b128 v[16:19], v28
	ds_read_b128 v[20:23], v28 offset:1024
	ds_read_b128 v[24:27], v28 offset:2048
	ds_read_b128 v[28:31], v28 offset:3072
	s_add_u32 s24, s64, 0x158000
	s_addc_u32 s25, s65, 0
	s_mov_b32 m0, s49
	ds_read_b128 v[194:197], v193 offset:32768
	ds_read_b128 v[198:201], v193 offset:33792
	ds_read_b128 v[202:205], v193 offset:34816
	ds_read_b128 v[206:209], v193 offset:35840
	ds_read_b128 v[210:213], v193 offset:36864
	ds_read_b128 v[214:217], v193 offset:37888
	ds_read_b128 v[218:221], v193 offset:38912
	ds_read_b128 v[222:225], v193 offset:39936
	global_load_lds_dwordx4 v160, s[24:25]
	s_mov_b32 m0, s69
	s_nop 0
	global_load_lds_dwordx4 v162, s[24:25]
	s_waitcnt vmcnt(8)
	s_waitcnt lgkmcnt(0)
	s_barrier
	s_setprio 1
	s_waitcnt lgkmcnt(0)
	v_mfma_f32_16x16x128_f8f6f4 v[156:159], v[0:7], v[194:201], v[156:159]
	v_mfma_f32_16x16x128_f8f6f4 v[152:155], v[8:15], v[194:201], v[152:155]
	v_mfma_f32_16x16x128_f8f6f4 v[148:151], v[0:7], v[202:209], v[148:151]
	v_mfma_f32_16x16x128_f8f6f4 v[140:143], v[8:15], v[202:209], v[140:143]
	v_mfma_f32_16x16x128_f8f6f4 v[132:135], v[0:7], v[210:217], v[132:135]
	v_mfma_f32_16x16x128_f8f6f4 v[124:127], v[8:15], v[210:217], v[124:127]
	v_mfma_f32_16x16x128_f8f6f4 v[116:119], v[0:7], v[218:225], v[116:119]
	v_mfma_f32_16x16x128_f8f6f4 v[108:111], v[8:15], v[218:225], v[108:111]
	s_setprio 0
	s_setprio 1
	v_mfma_f32_16x16x128_f8f6f4 v[144:147], v[16:23], v[194:201], v[144:147]
	v_mfma_f32_16x16x128_f8f6f4 v[136:139], v[24:31], v[194:201], v[136:139]
	v_mfma_f32_16x16x128_f8f6f4 v[128:131], v[16:23], v[202:209], v[128:131]
	v_mfma_f32_16x16x128_f8f6f4 v[120:123], v[24:31], v[202:209], v[120:123]
	v_mfma_f32_16x16x128_f8f6f4 v[112:115], v[16:23], v[210:217], v[112:115]
	v_mfma_f32_16x16x128_f8f6f4 v[104:107], v[24:31], v[210:217], v[104:107]
	v_mfma_f32_16x16x128_f8f6f4 v[100:103], v[16:23], v[218:225], v[100:103]
	v_mfma_f32_16x16x128_f8f6f4 v[96:99], v[24:31], v[218:225], v[96:99]
	s_setprio 0
	s_barrier
	s_add_i32 s24, s58, s93
	s_add_i32 m0, s24, 0xffffff80
	ds_read_b128 v[194:197], v193 offset:49152
	ds_read_b128 v[198:201], v193 offset:50176
	ds_read_b128 v[202:205], v193 offset:51200
	ds_read_b128 v[206:209], v193 offset:52224
	ds_read_b128 v[210:213], v193 offset:53248
	ds_read_b128 v[214:217], v193 offset:54272
	ds_read_b128 v[218:221], v193 offset:55296
	ds_read_b128 v[222:225], v193 offset:56320
	global_load_lds_dwordx4 v160, s[62:63] offset:128
	s_add_i32 m0, s24, 0x1f80
	s_add_u32 s24, s62, 0x158080
	s_addc_u32 s25, s63, 0
	s_add_i32 s58, s59, s93
	global_load_lds_dwordx4 v162, s[62:63] offset:128
	s_mov_b32 m0, s58
	s_nop 0
	global_load_lds_dwordx4 v160, s[24:25]
	s_add_i32 m0, s58, 0x2000
	s_nop 0
	global_load_lds_dwordx4 v162, s[24:25]
	s_add_i32 m0, s79, 0xffffff80
	s_nop 0
	global_load_lds_dwordx4 v160, s[64:65] offset:128
	s_add_i32 m0, s80, 0xffffff80
	s_nop 0
	global_load_lds_dwordx4 v162, s[64:65] offset:128
	s_waitcnt vmcnt(8)
	s_waitcnt lgkmcnt(0)
	s_barrier
	s_setprio 1
	s_waitcnt lgkmcnt(0)
	v_mfma_f32_16x16x128_f8f6f4 v[92:95], v[0:7], v[194:201], v[92:95]
	v_mfma_f32_16x16x128_f8f6f4 v[88:91], v[8:15], v[194:201], v[88:91]
	v_mfma_f32_16x16x128_f8f6f4 v[84:87], v[0:7], v[202:209], v[84:87]
	v_mfma_f32_16x16x128_f8f6f4 v[72:75], v[8:15], v[202:209], v[72:75]
	v_mfma_f32_16x16x128_f8f6f4 v[68:71], v[0:7], v[210:217], v[68:71]
	v_mfma_f32_16x16x128_f8f6f4 v[56:59], v[8:15], v[210:217], v[56:59]
	v_mfma_f32_16x16x128_f8f6f4 v[52:55], v[0:7], v[218:225], v[52:55]
	v_mfma_f32_16x16x128_f8f6f4 v[40:43], v[8:15], v[218:225], v[40:43]
	s_setprio 0
	s_setprio 1
	v_mfma_f32_16x16x128_f8f6f4 v[80:83], v[16:23], v[194:201], v[80:83]
	v_mfma_f32_16x16x128_f8f6f4 v[76:79], v[24:31], v[194:201], v[76:79]
	v_mfma_f32_16x16x128_f8f6f4 v[64:67], v[16:23], v[202:209], v[64:67]
	v_mfma_f32_16x16x128_f8f6f4 v[60:63], v[24:31], v[202:209], v[60:63]
	v_mfma_f32_16x16x128_f8f6f4 v[48:51], v[16:23], v[210:217], v[48:51]
	v_mfma_f32_16x16x128_f8f6f4 v[44:47], v[24:31], v[210:217], v[44:47]
	v_mfma_f32_16x16x128_f8f6f4 v[36:39], v[16:23], v[218:225], v[36:39]
	v_mfma_f32_16x16x128_f8f6f4 v[32:35], v[24:31], v[218:225], v[32:35]
	s_add_u32 s97, s97, 0x100
	s_addc_u32 vcc_lo, vcc_lo, 0
	s_cmp_ge_i32 vcc_hi, s96
	s_mov_b64 s[58:59], s[60:61]
	s_mov_b32 s62, vcc_hi
	s_setprio 0
	s_barrier
	s_cbranch_scc0 .LBB0_1444
	s_nop 15
	s_nop 15
	s_and_b64 vcc, exec, s[94:95]
	s_cbranch_vccz .LBB0_1447
	s_barrier

.LBB0_1588:
	ds_read_b128 v[24:27], v218
	ds_read_b128 v[28:31], v218 offset:1024
	ds_read_b128 v[16:19], v218 offset:2048
	ds_read_b128 v[20:23], v218 offset:3072
	ds_read_b128 v[8:11], v219
	ds_read_b128 v[12:15], v219 offset:1024
	ds_read_b128 v[0:3], v219 offset:2048
	ds_read_b128 v[4:7], v219 offset:3072
	s_add_i32 s79, s52, 2
	s_add_u32 s53, s50, 0xfff80080
	s_addc_u32 s54, s51, -1
	s_cmp_eq_u32 s76, s52
	s_cselect_b32 s52, s75, s77
	s_cselect_b32 s55, s31, s54
	s_cselect_b32 s54, s37, s53
	s_cselect_b32 s53, s35, s78
	s_add_i32 m0, s47, 0xc000
	ds_read_b128 v[160:163], v220
	ds_read_b128 v[164:167], v220 offset:1024
	ds_read_b128 v[168:171], v220 offset:2048
	ds_read_b128 v[172:175], v220 offset:3072
	ds_read_b128 v[176:179], v220 offset:4096
	ds_read_b128 v[180:183], v220 offset:5120
	ds_read_b128 v[184:187], v220 offset:6144
	ds_read_b128 v[188:191], v220 offset:7168
	global_load_lds_dwordx4 v196, s[50:51]
	s_add_i32 m0, s47, 0xe000
	s_nop 0
	global_load_lds_dwordx4 v198, s[50:51]
	s_waitcnt vmcnt(8)
	s_waitcnt lgkmcnt(0)
	s_barrier
	s_setprio 1
	s_waitcnt lgkmcnt(0)
	v_mfma_f32_16x16x128_f8f6f4 v[156:159], v[24:31], v[160:167], v[156:159]
	v_mfma_f32_16x16x128_f8f6f4 v[152:155], v[16:23], v[160:167], v[152:155]
	v_mfma_f32_16x16x128_f8f6f4 v[148:151], v[24:31], v[168:175], v[148:151]
	v_mfma_f32_16x16x128_f8f6f4 v[140:143], v[16:23], v[168:175], v[140:143]
	v_mfma_f32_16x16x128_f8f6f4 v[132:135], v[24:31], v[176:183], v[132:135]
	v_mfma_f32_16x16x128_f8f6f4 v[124:127], v[16:23], v[176:183], v[124:127]
	v_mfma_f32_16x16x128_f8f6f4 v[116:119], v[24:31], v[184:191], v[116:119]
	v_mfma_f32_16x16x128_f8f6f4 v[108:111], v[16:23], v[184:191], v[108:111]
	s_setprio 0
	s_setprio 1
	v_mfma_f32_16x16x128_f8f6f4 v[144:147], v[8:15], v[160:167], v[144:147]
	v_mfma_f32_16x16x128_f8f6f4 v[136:139], v[0:7], v[160:167], v[136:139]
	v_mfma_f32_16x16x128_f8f6f4 v[128:131], v[8:15], v[168:175], v[128:131]
	v_mfma_f32_16x16x128_f8f6f4 v[120:123], v[0:7], v[168:175], v[120:123]
	v_mfma_f32_16x16x128_f8f6f4 v[112:115], v[8:15], v[176:183], v[112:115]
	v_mfma_f32_16x16x128_f8f6f4 v[104:107], v[0:7], v[176:183], v[104:107]
	v_mfma_f32_16x16x128_f8f6f4 v[100:103], v[8:15], v[184:191], v[100:103]
	v_mfma_f32_16x16x128_f8f6f4 v[96:99], v[0:7], v[184:191], v[96:99]
	s_setprio 0
	s_barrier
	s_add_i32 s80, s66, s93
	s_mov_b32 m0, s80
	ds_read_b128 v[168:171], v220 offset:16384
	ds_read_b128 v[172:175], v220 offset:17408
	ds_read_b128 v[176:179], v220 offset:18432
	ds_read_b128 v[180:183], v220 offset:19456
	ds_read_b128 v[184:187], v220 offset:20480
	ds_read_b128 v[188:191], v220 offset:21504
	ds_read_b128 v[202:205], v220 offset:22528
	ds_read_b128 v[206:209], v220 offset:23552
	global_load_lds_dwordx4 v192, s[52:53]
	s_add_i32 m0, s80, 0x2000
	s_add_u32 s80, s52, 0x80000
	v_lshl_add_u64 v[162:163], s[52:53], 0, v[194:195]
	s_addc_u32 s81, s53, 0
	s_add_i32 s82, s68, s93
	global_load_lds_dwordx4 v194, s[52:53]
	s_mov_b32 m0, s82
	v_lshl_add_u64 v[166:167], s[54:55], 0, v[194:195]
	global_load_lds_dwordx4 v192, s[80:81]
	s_add_i32 m0, s82, 0x2000
	s_nop 0
	global_load_lds_dwordx4 v194, s[80:81]
	v_lshl_add_u64 v[164:165], s[54:55], 0, v[192:193]
	s_mov_b32 m0, s47
	s_nop 0
	global_load_lds_dwordx4 v192, s[54:55]
	s_mov_b32 m0, s58
	s_nop 0
	global_load_lds_dwordx4 v194, s[54:55]
	s_waitcnt vmcnt(8)
	s_waitcnt lgkmcnt(0)
	s_barrier
	s_setprio 1
	s_waitcnt lgkmcnt(0)
	v_mfma_f32_16x16x128_f8f6f4 v[92:95], v[24:31], v[168:175], v[92:95]
	v_mfma_f32_16x16x128_f8f6f4 v[88:91], v[16:23], v[168:175], v[88:91]
	v_mfma_f32_16x16x128_f8f6f4 v[84:87], v[24:31], v[176:183], v[84:87]
	v_mfma_f32_16x16x128_f8f6f4 v[72:75], v[16:23], v[176:183], v[72:75]
	v_mfma_f32_16x16x128_f8f6f4 v[68:71], v[24:31], v[184:191], v[68:71]
	v_mfma_f32_16x16x128_f8f6f4 v[56:59], v[16:23], v[184:191], v[56:59]
	v_mfma_f32_16x16x128_f8f6f4 v[52:55], v[24:31], v[202:209], v[52:55]
	v_mfma_f32_16x16x128_f8f6f4 v[44:47], v[16:23], v[202:209], v[44:47]
	s_setprio 0
	s_setprio 1
	v_mfma_f32_16x16x128_f8f6f4 v[80:83], v[8:15], v[168:175], v[80:83]
	v_mfma_f32_16x16x128_f8f6f4 v[76:79], v[0:7], v[168:175], v[76:79]
	v_mfma_f32_16x16x128_f8f6f4 v[64:67], v[8:15], v[176:183], v[64:67]
	v_mfma_f32_16x16x128_f8f6f4 v[60:63], v[0:7], v[176:183], v[60:63]
	v_mfma_f32_16x16x128_f8f6f4 v[48:51], v[8:15], v[184:191], v[48:51]
	v_mfma_f32_16x16x128_f8f6f4 v[40:43], v[0:7], v[184:191], v[40:43]
	v_mfma_f32_16x16x128_f8f6f4 v[36:39], v[8:15], v[202:209], v[36:39]
	v_mfma_f32_16x16x128_f8f6f4 v[32:35], v[0:7], v[202:209], v[32:35]
	s_setprio 0
	s_barrier
	s_add_i32 s80, 0, 0x18000
	s_add_i32 s81, 0, 0x1c000
	v_add_u32_e32 v12, s80, v215
	v_add_u32_e32 v28, s81, v215
	ds_read_b128 v[0:3], v12
	ds_read_b128 v[4:7], v12 offset:1024
	ds_read_b128 v[8:11], v12 offset:2048
	ds_read_b128 v[12:15], v12 offset:3072
	ds_read_b128 v[16:19], v28
	ds_read_b128 v[20:23], v28 offset:1024
	ds_read_b128 v[24:27], v28 offset:2048
	ds_read_b128 v[28:31], v28 offset:3072
	s_add_u32 s54, s54, 0x80000
	s_addc_u32 s55, s55, 0
	s_mov_b32 m0, s59
	ds_read_b128 v[168:171], v220 offset:32768
	ds_read_b128 v[172:175], v220 offset:33792
	ds_read_b128 v[176:179], v220 offset:34816
	ds_read_b128 v[180:183], v220 offset:35840
	ds_read_b128 v[184:187], v220 offset:36864
	ds_read_b128 v[188:191], v220 offset:37888
	ds_read_b128 v[202:205], v220 offset:38912
	ds_read_b128 v[206:209], v220 offset:39936
	global_load_lds_dwordx4 v192, s[54:55]
	s_mov_b32 m0, s60
	s_nop 0
	global_load_lds_dwordx4 v194, s[54:55]
	s_waitcnt vmcnt(8)
	s_waitcnt lgkmcnt(0)
	s_barrier
	s_setprio 1
	s_waitcnt lgkmcnt(0)
	v_mfma_f32_16x16x128_f8f6f4 v[156:159], v[0:7], v[168:175], v[156:159]
	v_mfma_f32_16x16x128_f8f6f4 v[152:155], v[8:15], v[168:175], v[152:155]
	v_mfma_f32_16x16x128_f8f6f4 v[148:151], v[0:7], v[176:183], v[148:151]
	v_mfma_f32_16x16x128_f8f6f4 v[140:143], v[8:15], v[176:183], v[140:143]
	v_mfma_f32_16x16x128_f8f6f4 v[132:135], v[0:7], v[184:191], v[132:135]
	v_mfma_f32_16x16x128_f8f6f4 v[124:127], v[8:15], v[184:191], v[124:127]
	v_mfma_f32_16x16x128_f8f6f4 v[116:119], v[0:7], v[202:209], v[116:119]
	v_mfma_f32_16x16x128_f8f6f4 v[108:111], v[8:15], v[202:209], v[108:111]
	s_setprio 0
	s_setprio 1
	v_mfma_f32_16x16x128_f8f6f4 v[144:147], v[16:23], v[168:175], v[144:147]
	v_mfma_f32_16x16x128_f8f6f4 v[136:139], v[24:31], v[168:175], v[136:139]
	v_mfma_f32_16x16x128_f8f6f4 v[128:131], v[16:23], v[176:183], v[128:131]
	v_mfma_f32_16x16x128_f8f6f4 v[120:123], v[24:31], v[176:183], v[120:123]
	v_mfma_f32_16x16x128_f8f6f4 v[112:115], v[16:23], v[184:191], v[112:115]
	v_mfma_f32_16x16x128_f8f6f4 v[104:107], v[24:31], v[184:191], v[104:107]
	v_mfma_f32_16x16x128_f8f6f4 v[100:103], v[16:23], v[202:209], v[100:103]
	v_mfma_f32_16x16x128_f8f6f4 v[96:99], v[24:31], v[202:209], v[96:99]
	s_setprio 0
	s_barrier
	s_add_i32 s54, s80, s93
	s_add_i32 m0, s54, 0xffffff80
	ds_read_b128 v[168:171], v220 offset:49152
	ds_read_b128 v[172:175], v220 offset:50176
	ds_read_b128 v[176:179], v220 offset:51200
	ds_read_b128 v[180:183], v220 offset:52224
	ds_read_b128 v[184:187], v220 offset:53248
	ds_read_b128 v[188:191], v220 offset:54272
	ds_read_b128 v[202:205], v220 offset:55296
	ds_read_b128 v[206:209], v220 offset:56320
	global_load_lds_dwordx4 v192, s[52:53] offset:128
	s_add_i32 m0, s54, 0x2000
	s_add_u32 s52, s52, 0x80080
	v_lshl_add_u64 v[160:161], v[162:163], 0, s[24:25]
	s_addc_u32 s53, s53, 0
	s_add_i32 s54, s81, s93
	global_load_lds_dwordx4 v[160:161], off
	s_mov_b32 m0, s54
	s_nop 0
	global_load_lds_dwordx4 v192, s[52:53]
	s_add_i32 m0, s54, 0x2000
	s_nop 0
	global_load_lds_dwordx4 v194, s[52:53]
	v_lshl_add_u64 v[160:161], v[164:165], 0, s[24:25]
	s_mov_b32 m0, s64
	s_nop 0
	global_load_lds_dwordx4 v[160:161], off
	v_lshl_add_u64 v[160:161], v[166:167], 0, s[24:25]
	s_mov_b32 m0, s65
	s_nop 0
	global_load_lds_dwordx4 v[160:161], off
	s_waitcnt vmcnt(8)
	s_waitcnt lgkmcnt(0)
	s_barrier
	s_setprio 1
	s_waitcnt lgkmcnt(0)
	v_mfma_f32_16x16x128_f8f6f4 v[92:95], v[0:7], v[168:175], v[92:95]
	v_mfma_f32_16x16x128_f8f6f4 v[88:91], v[8:15], v[168:175], v[88:91]
	v_mfma_f32_16x16x128_f8f6f4 v[84:87], v[0:7], v[176:183], v[84:87]
	v_mfma_f32_16x16x128_f8f6f4 v[72:75], v[8:15], v[176:183], v[72:75]
	v_mfma_f32_16x16x128_f8f6f4 v[68:71], v[0:7], v[184:191], v[68:71]
	v_mfma_f32_16x16x128_f8f6f4 v[56:59], v[8:15], v[184:191], v[56:59]
	v_mfma_f32_16x16x128_f8f6f4 v[52:55], v[0:7], v[202:209], v[52:55]
	v_mfma_f32_16x16x128_f8f6f4 v[44:47], v[8:15], v[202:209], v[44:47]
	s_setprio 0
	s_setprio 1
	v_mfma_f32_16x16x128_f8f6f4 v[80:83], v[16:23], v[168:175], v[80:83]
	v_mfma_f32_16x16x128_f8f6f4 v[76:79], v[24:31], v[168:175], v[76:79]
	v_mfma_f32_16x16x128_f8f6f4 v[64:67], v[16:23], v[176:183], v[64:67]
	v_mfma_f32_16x16x128_f8f6f4 v[60:63], v[24:31], v[176:183], v[60:63]
	v_mfma_f32_16x16x128_f8f6f4 v[48:51], v[16:23], v[184:191], v[48:51]
	v_mfma_f32_16x16x128_f8f6f4 v[40:43], v[24:31], v[184:191], v[40:43]
	v_mfma_f32_16x16x128_f8f6f4 v[36:39], v[16:23], v[202:209], v[36:39]
	v_mfma_f32_16x16x128_f8f6f4 v[32:35], v[24:31], v[202:209], v[32:35]
	s_add_u32 s50, s50, 0x100
	s_addc_u32 s51, s51, 0
	s_add_u32 s77, s77, 0x100
	s_addc_u32 s78, s78, 0
	s_cmp_ge_i32 s79, s45
	s_mov_b32 s52, s79
	s_setprio 0
	s_barrier
	s_cbranch_scc0 .LBB0_1588
	s_nop 15
	s_nop 15
	s_andn2_b64 vcc, exec, s[48:49]
	s_cbranch_vccnz .LBB0_1602
	global_load_dword v0, v193, s[6:7] sc1
	s_waitcnt vmcnt(0)
	v_cmp_le_u32_e32 vcc, s88, v0
	s_cbranch_vccnz .LBB0_1601
	s_mov_b32 s31, 0x3ffff8
	s_branch .LBB0_1593
